# merge epilogue: once-read gate loads marked nt (streaming) so they do not displace the reused y / weight lines in L2
# speedup vs baseline: 1.0139x; 1.0002x over previous
; template <int NI, class LA, class LB, class EP>
; __device__ __forceinline__ void gemm_tile(int K, LA loadA, LB loadB, EP epi, char* smem) {
;     ...
;   for (int kt = 0; kt < nk; ++kt) {
;     __syncthreads();
; #pragma unroll
;     for (int i = 0; i < 4; ++i) *(uint4*)&sA[(lr + 32 * i) * 72 + lc] = ra[i];
; #pragma unroll
;     for (int i = 0; i < NB; ++i) *(uint4*)&sB[(lr + 32 * i) * 72 + lc] = rb[i];
;     __syncthreads();
;     if (kt + 1 < nk) {
;       const int kk = (kt + 1) * 64 + lc;
; #pragma unroll
;       for (int i = 0; i < 4; ++i) ra[i] = loadA(lr + 32 * i, kk);
; #pragma unroll
;       for (int i = 0; i < NB; ++i) rb[i] = loadB(lr + 32 * i, kk);
;     }
; #pragma unroll
;     for (int s = 0; s < 4; ++s) {
;       h8 af[2], bf[NI];
; #pragma unroll
;       for (int mi = 0; mi < 2; ++mi)
;         af[mi] = *(const h8*)&sA[(wm * 64 + mi * 32 + (lane & 31)) * 72 + s * 16 + (lane >> 5) * 8];
; #pragma unroll
;       for (int ni = 0; ni < NI; ++ni)
;         bf[ni] = *(const h8*)&sB[(wn * (NI * 32) + ni * 32 + (lane & 31)) * 72 + s * 16 + (lane >> 5) * 8];
; #pragma unroll
;       for (int mi = 0; mi < 2; ++mi)
; #pragma unroll
;         for (int ni = 0; ni < NI; ++ni)
;           acc[mi][ni] = __builtin_amdgcn_mfma_f32_32x32x16_f16(af[mi], bf[ni], acc[mi][ni], 0, 0, 0);
;     }
.LBB0_1743:
	s_waitcnt vmcnt(63) expcnt(7) lgkmcnt(15)
	s_barrier
	s_waitcnt vmcnt(7)
	ds_write_b128 v172, v[192:195]
	s_waitcnt vmcnt(6)
	ds_write_b128 v172, v[196:199] offset:4608
	s_waitcnt vmcnt(5)
	ds_write_b128 v172, v[200:203] offset:9216
	s_waitcnt vmcnt(4)
	ds_write_b128 v172, v[204:207] offset:13824
	s_waitcnt vmcnt(3)
	ds_write_b128 v172, v[208:211] offset:18432
	s_waitcnt vmcnt(2)
	ds_write_b128 v172, v[212:215] offset:23040
	s_waitcnt vmcnt(1)
	ds_write_b128 v172, v[216:219] offset:27648
	s_waitcnt vmcnt(0)
	ds_write_b128 v172, v[220:223] offset:32256
	global_load_dwordx4 v[192:195], v[228:229], off
	global_load_dwordx4 v[196:199], v[230:231], off
	global_load_dwordx4 v[200:203], v[232:233], off
	global_load_dwordx4 v[204:207], v[234:235], off
	global_load_dwordx4 v[208:211], v[238:239], off
	global_load_dwordx4 v[212:215], v[240:241], off
	global_load_dwordx4 v[216:219], v[242:243], off
	global_load_dwordx4 v[220:223], v[244:245], off
	s_waitcnt lgkmcnt(0)
	s_barrier
	ds_read_b128 v[66:69], v162
	ds_read_b128 v[70:73], v163 offset:18432
	ds_read_b128 v[74:77], v162 offset:32
	ds_read_b128 v[78:81], v163 offset:18464
	ds_read_b128 v[82:85], v171 offset:18432
	ds_read_b128 v[174:177], v163 offset:23136
	s_waitcnt lgkmcnt(4)
	v_mfma_f32_32x32x16_f16 v[50:65], v[66:69], v[70:73], v[50:65]
	s_waitcnt lgkmcnt(1)
	v_mfma_f32_32x32x16_f16 v[34:49], v[66:69], v[82:85], v[34:49]
	v_lshl_add_u64 v[228:229], v[228:229], 0, s[2:3]
	ds_read_b128 v[66:69], v162 offset:4608
	ds_read_b128 v[86:89], v162 offset:4640
	s_waitcnt lgkmcnt(1)
	v_mfma_f32_32x32x16_f16 v[18:33], v[66:69], v[70:73], v[18:33]
	v_mfma_f32_32x32x16_f16 v[2:17], v[66:69], v[82:85], v[2:17]
	v_lshl_add_u64 v[230:231], v[230:231], 0, s[2:3]
	ds_read_b128 v[66:69], v163 offset:23072
	ds_read_b128 v[70:73], v163 offset:23104
	v_mfma_f32_32x32x16_f16 v[50:65], v[74:77], v[78:81], v[50:65]
	s_waitcnt lgkmcnt(1)
	v_mfma_f32_32x32x16_f16 v[34:49], v[74:77], v[66:69], v[34:49]
	v_lshl_add_u64 v[232:233], v[232:233], 0, s[2:3]
	v_mfma_f32_32x32x16_f16 v[18:33], v[86:89], v[78:81], v[18:33]
	v_mfma_f32_32x32x16_f16 v[2:17], v[86:89], v[66:69], v[2:17]
	v_lshl_add_u64 v[234:235], v[234:235], 0, s[2:3]
	ds_read_b128 v[66:69], v162 offset:64
	ds_read_b128 v[74:77], v163 offset:18496
	ds_read_b128 v[78:81], v162 offset:96
	ds_read_b128 v[82:85], v163 offset:18528
	ds_read_b128 v[86:89], v162 offset:4672
	ds_read_b128 v[178:181], v162 offset:4704
	s_waitcnt lgkmcnt(4)
	v_mfma_f32_32x32x16_f16 v[50:65], v[66:69], v[74:77], v[50:65]
	v_mfma_f32_32x32x16_f16 v[34:49], v[66:69], v[70:73], v[34:49]
	v_lshl_add_u64 v[238:239], v[238:239], 0, s[2:3]
	s_waitcnt lgkmcnt(1)
	v_mfma_f32_32x32x16_f16 v[18:33], v[86:89], v[74:77], v[18:33]
	v_mfma_f32_32x32x16_f16 v[2:17], v[86:89], v[70:73], v[2:17]
	v_lshl_add_u64 v[240:241], v[240:241], 0, s[2:3]
	v_mfma_f32_32x32x16_f16 v[50:65], v[78:81], v[82:85], v[50:65]
	v_mfma_f32_32x32x16_f16 v[34:49], v[78:81], v[174:177], v[34:49]
	v_lshl_add_u64 v[242:243], v[242:243], 0, s[2:3]
	s_waitcnt lgkmcnt(0)
	v_mfma_f32_32x32x16_f16 v[18:33], v[178:181], v[82:85], v[18:33]
	v_mfma_f32_32x32x16_f16 v[2:17], v[178:181], v[174:177], v[2:17]
	v_lshl_add_u64 v[244:245], v[244:245], 0, s[2:3]
	s_add_u32 s40, s40, 0x80
	s_addc_u32 s41, s41, 0
	s_cmpk_lg_i32 s40, 0x380
	s_cbranch_scc1 .LBB0_1743
	s_barrier
	s_waitcnt vmcnt(7)
	ds_write_b128 v172, v[192:195]
	s_waitcnt vmcnt(6)
	ds_write_b128 v172, v[196:199] offset:4608
	s_waitcnt vmcnt(5)
	ds_write_b128 v172, v[200:203] offset:9216
	s_waitcnt vmcnt(4)
	ds_write_b128 v172, v[204:207] offset:13824
	s_waitcnt vmcnt(3)
	ds_write_b128 v172, v[208:211] offset:18432
	s_waitcnt vmcnt(2)
	ds_write_b128 v172, v[212:215] offset:23040
	s_waitcnt vmcnt(1)
	ds_write_b128 v172, v[216:219] offset:27648
	s_waitcnt vmcnt(0)
	ds_write_b128 v172, v[220:223] offset:32256
	s_waitcnt lgkmcnt(0)
	s_barrier
	ds_read_b128 v[66:69], v162 offset:4608
	ds_read_b128 v[70:73], v171 offset:18432
	ds_read_b128 v[74:77], v162
	ds_read_b128 v[78:81], v162 offset:32
	ds_read_b128 v[82:85], v163 offset:18432
	ds_read_b128 v[86:89], v163 offset:18464
	s_waitcnt lgkmcnt(1)
	v_mfma_f32_32x32x16_f16 v[50:65], v[74:77], v[82:85], v[50:65]
	s_lshl_b32 s2, s56, 11
	s_add_u32 s2, s52, s2
	s_addc_u32 s3, s53, 0
	v_lshlrev_b32_e32 v0, 1, v0
	s_add_i32 s56, s56, 1
	s_add_u32 s38, s38, 0x100000
	s_addc_u32 s39, s39, 0
	v_mfma_f32_32x32x16_f16 v[34:49], v[74:77], v[70:73], v[34:49]
	s_cmp_lg_u32 s56, 3
	v_mfma_f32_32x32x16_f16 v[18:33], v[66:69], v[82:85], v[18:33]
	v_mfma_f32_32x32x16_f16 v[2:17], v[66:69], v[70:73], v[2:17]
	ds_read_b128 v[66:69], v162 offset:4640
	ds_read_b128 v[70:73], v163 offset:23072
	s_waitcnt lgkmcnt(2)
	v_mfma_f32_32x32x16_f16 v[50:65], v[78:81], v[86:89], v[50:65]
	s_waitcnt lgkmcnt(0)
	v_mfma_f32_32x32x16_f16 v[34:49], v[78:81], v[70:73], v[34:49]
	v_mfma_f32_32x32x16_f16 v[18:33], v[66:69], v[86:89], v[18:33]
	v_mfma_f32_32x32x16_f16 v[2:17], v[66:69], v[70:73], v[2:17]
	ds_read_b128 v[66:69], v162 offset:64
	ds_read_b128 v[70:73], v162 offset:4672
	ds_read_b128 v[74:77], v163 offset:18496
	ds_read_b128 v[78:81], v163 offset:23104
	s_waitcnt lgkmcnt(1)
	v_mfma_f32_32x32x16_f16 v[50:65], v[66:69], v[74:77], v[50:65]
	s_waitcnt lgkmcnt(0)
	v_mfma_f32_32x32x16_f16 v[34:49], v[66:69], v[78:81], v[34:49]
	v_mfma_f32_32x32x16_f16 v[18:33], v[70:73], v[74:77], v[18:33]
	v_mfma_f32_32x32x16_f16 v[2:17], v[70:73], v[78:81], v[2:17]
	ds_read_b128 v[66:69], v162 offset:96
	ds_read_b128 v[70:73], v162 offset:4704
	ds_read_b128 v[74:77], v163 offset:18528
	ds_read_b128 v[78:81], v163 offset:23136
	s_waitcnt lgkmcnt(1)
;   __device__ __forceinline__ const float* x() const { return (const float*)(const __attribute__((address_space(1))) float*)kp[0]; }
;   __device__ __forceinline__ half_t* u() const { return (half_t*)(ws() + OFF_u); }
; __device__ __forceinline__ float sigmoidf_(float x) { return 1.f / (1.f + __expf(-x)); }
; __device__ __forceinline__ void phase_merge(const KP& p, char* smem, int* q, int xcc) {
;     ...
;       const half_t* G = p.u() + (size_t)m0 * NU + C_GM + br * 1024 + n0;
;       gemm_tile<2>(
;           512, [&](int r, int k) { return *(const uint4*)(A + (size_t)r * 512 + k); },
;           [&](int r, int k) { return *(const uint4*)(B + (size_t)r * 512 + k); },
;           [&](int mi, int ni, int r, int row, int col, float v) {
;             const float gz = (float)G[(size_t)row * NU + col];
;             tot[mi][ni][r] += sigmoidf_(gz) * v;
	v_mfma_f32_32x32x16_f16 v[50:65], v[66:69], v[74:77], v[50:65]
	s_waitcnt lgkmcnt(0)
	v_mfma_f32_32x32x16_f16 v[34:49], v[66:69], v[78:81], v[34:49]
	v_mfma_f32_32x32x16_f16 v[18:33], v[70:73], v[74:77], v[18:33]
	v_mfma_f32_32x32x16_f16 v[2:17], v[70:73], v[78:81], v[2:17]
	v_mov_b32_e32 v228, 0x11fe4
	v_mov_b32_e32 v229, 0x100
	v_mov_b32_e32 v230, 2
	v_mov_b32_e32 v231, 0x3727c5ac
	v_mov_b32_e32 v232, 0x11fa0
	v_mov_b32_e32 v233, 0x80000
	v_mov_b32_e32 v234, 0x1d0000
	v_mov_b32_e32 v235, 0xa800
	v_mov_b32_e32 v238, 0x4000
	v_mov_b32_e32 v239, 0x4400
	v_mov_b32_e32 v240, 0x4800
	v_mov_b32_e32 v241, 0x4c00
	v_mov_b32_e32 v242, 0xf149f2ca
	v_mov_b32_e32 v243, 0x200
	v_mov_b32_e32 v244, 0x400
	v_mov_b32_e32 v245, 0x600
	v_lshrrev_b32_e32 v94, 7, v224
	v_lshlrev_b32_e32 v94, 4, v94
	v_bfe_u32 v95, v224, 5, 1
	v_add_u32_e32 v94, v94, v95
	v_mul_u32_u24_e32 v94, 0xe800, v94
	v_bfe_u32 v95, v224, 6, 1
	v_lshl_add_u32 v94, v95, 7, v94
	v_and_b32_e32 v95, 31, v224
	v_lshl_add_u32 v94, v95, 1, v94
	s_mov_b64 s[40:41], s[2:3]
	v_mov_b32_e32 v96, v94
	global_load_ushort v192, v96, s[40:41] nt
	v_add_u32_e32 v96, 0x3a00, v94
	global_load_ushort v193, v96, s[40:41] nt
	v_add_u32_e32 v96, 0x7400, v94
	global_load_ushort v194, v96, s[40:41] nt
	v_add_u32_e32 v96, 0xae00, v94
	global_load_ushort v195, v96, s[40:41] nt
	v_add_u32_e32 v96, 0x1d000, v94
	global_load_ushort v196, v96, s[40:41] nt
	v_add_u32_e32 v96, 0x20a00, v94
	global_load_ushort v197, v96, s[40:41] nt
	v_add_u32_e32 v96, 0x24400, v94
	global_load_ushort v198, v96, s[40:41] nt
	v_add_u32_e32 v96, 0x27e00, v94
	global_load_ushort v199, v96, s[40:41] nt
	v_add_u32_e32 v96, 0x3a000, v94
	global_load_ushort v200, v96, s[40:41] nt
	v_add_u32_e32 v96, 0x3da00, v94
	global_load_ushort v201, v96, s[40:41] nt
	v_add_u32_e32 v96, 0x41400, v94
	global_load_ushort v202, v96, s[40:41] nt
	v_add_u32_e32 v96, 0x44e00, v94
	global_load_ushort v203, v96, s[40:41] nt
	v_add_u32_e32 v96, 0x57000, v94
	global_load_ushort v204, v96, s[40:41] nt
	v_add_u32_e32 v96, 0x5aa00, v94
	global_load_ushort v205, v96, s[40:41] nt
	v_add_u32_e32 v96, 0x5e400, v94
	global_load_ushort v206, v96, s[40:41] nt
	v_add_u32_e32 v96, 0x61e00, v94
	global_load_ushort v207, v96, s[40:41] nt
	v_mov_b32_e32 v96, v94
	global_load_ushort v208, v96, s[40:41] offset:64 nt
	v_add_u32_e32 v96, 0x3a00, v94
	global_load_ushort v209, v96, s[40:41] offset:64 nt
	v_add_u32_e32 v96, 0x7400, v94
	global_load_ushort v210, v96, s[40:41] offset:64 nt
	v_add_u32_e32 v96, 0xae00, v94
	global_load_ushort v211, v96, s[40:41] offset:64 nt
	v_add_u32_e32 v96, 0x1d000, v94
	global_load_ushort v212, v96, s[40:41] offset:64 nt
	v_add_u32_e32 v96, 0x20a00, v94
	global_load_ushort v213, v96, s[40:41] offset:64 nt
	v_add_u32_e32 v96, 0x24400, v94
	global_load_ushort v214, v96, s[40:41] offset:64 nt
	v_add_u32_e32 v96, 0x27e00, v94
	global_load_ushort v215, v96, s[40:41] offset:64 nt
	v_add_u32_e32 v96, 0x3a000, v94
	global_load_ushort v216, v96, s[40:41] offset:64 nt
	v_add_u32_e32 v96, 0x3da00, v94
	global_load_ushort v217, v96, s[40:41] offset:64 nt
	v_add_u32_e32 v96, 0x41400, v94
	global_load_ushort v218, v96, s[40:41] offset:64 nt
	v_add_u32_e32 v96, 0x44e00, v94
	global_load_ushort v219, v96, s[40:41] offset:64 nt
	v_add_u32_e32 v96, 0x57000, v94
	global_load_ushort v220, v96, s[40:41] offset:64 nt
	v_add_u32_e32 v96, 0x5aa00, v94
	global_load_ushort v221, v96, s[40:41] offset:64 nt
	v_add_u32_e32 v96, 0x5e400, v94
	global_load_ushort v222, v96, s[40:41] offset:64 nt
	v_add_u32_e32 v96, 0x61e00, v94
	global_load_ushort v223, v96, s[40:41] offset:64 nt
	s_nop 7
	s_waitcnt vmcnt(30)
	v_cvt_f32_f16_e32 v68, v192
	v_cvt_f32_f16_e32 v69, v193
	v_add_u32_e32 v96, 0x74000, v94
	global_load_ushort v192, v96, s[40:41] nt
	v_add_u32_e32 v96, 0x77a00, v94
	global_load_ushort v193, v96, s[40:41] nt
	v_mul_f32_e32 v68, 0xbfb8aa3b, v68
	v_mul_f32_e32 v69, 0xbfb8aa3b, v69
	v_exp_f32_e32 v68, v68
	v_exp_f32_e32 v69, v69
	s_nop 0
	v_pk_add_f32 v[68:69], v[68:69], 1.0 op_sel_hi:[1,0]
	s_nop 0
	v_div_scale_f32 v70, s[2:3], v69, v69, 1.0
	v_rcp_f32_e32 v71, v70
	s_nop 0
	v_fma_f32 v72, -v70, v71, 1.0
	v_fmac_f32_e32 v71, v72, v71
	v_div_scale_f32 v72, vcc, 1.0, v69, 1.0
	v_mul_f32_e32 v73, v72, v71
	v_fma_f32 v74, -v70, v73, v72
	v_fmac_f32_e32 v73, v74, v71
	v_fma_f32 v70, -v70, v73, v72
	v_div_fmas_f32 v70, v70, v71, v73
	v_div_fixup_f32 v69, v70, v69, 1.0
	v_div_scale_f32 v70, s[2:3], v68, v68, 1.0
	v_rcp_f32_e32 v71, v70
	s_nop 0
	v_fma_f32 v72, -v70, v71, 1.0
	v_fmac_f32_e32 v71, v72, v71
	v_div_scale_f32 v72, vcc, 1.0, v68, 1.0
	v_mul_f32_e32 v73, v72, v71
	v_fma_f32 v74, -v70, v73, v72
	v_fmac_f32_e32 v73, v74, v71
	v_fma_f32 v70, -v70, v73, v72
	v_div_fmas_f32 v70, v70, v71, v73
	v_div_fixup_f32 v68, v70, v68, 1.0
	v_pk_fma_f32 v[160:161], v[50:51], v[68:69], v[160:161]
	s_waitcnt vmcnt(30)
	v_cvt_f32_f16_e32 v68, v194
	v_cvt_f32_f16_e32 v69, v195
	v_add_u32_e32 v96, 0x7b400, v94
	global_load_ushort v194, v96, s[40:41] nt
	v_add_u32_e32 v96, 0x7ee00, v94
	global_load_ushort v195, v96, s[40:41] nt
	v_mul_f32_e32 v68, 0xbfb8aa3b, v68
	v_mul_f32_e32 v69, 0xbfb8aa3b, v69
	v_exp_f32_e32 v68, v68
	v_exp_f32_e32 v69, v69
	s_nop 0
	v_pk_add_f32 v[68:69], v[68:69], 1.0 op_sel_hi:[1,0]
	s_nop 0
	v_div_scale_f32 v70, s[2:3], v69, v69, 1.0
	v_rcp_f32_e32 v71, v70
	s_nop 0
	v_fma_f32 v72, -v70, v71, 1.0
	v_fmac_f32_e32 v71, v72, v71
	v_div_scale_f32 v72, vcc, 1.0, v69, 1.0
	v_mul_f32_e32 v73, v72, v71
	v_fma_f32 v74, -v70, v73, v72
	v_fmac_f32_e32 v73, v74, v71
	v_fma_f32 v70, -v70, v73, v72
	v_div_fmas_f32 v70, v70, v71, v73
	v_div_fixup_f32 v69, v70, v69, 1.0
	v_div_scale_f32 v70, s[2:3], v68, v68, 1.0
	v_rcp_f32_e32 v71, v70
	s_nop 0
	v_fma_f32 v72, -v70, v71, 1.0
	v_fmac_f32_e32 v71, v72, v71
	v_div_scale_f32 v72, vcc, 1.0, v68, 1.0
	v_mul_f32_e32 v73, v72, v71
	v_fma_f32 v74, -v70, v73, v72
	v_fmac_f32_e32 v73, v74, v71
	v_fma_f32 v70, -v70, v73, v72
	v_div_fmas_f32 v70, v70, v71, v73
	v_div_fixup_f32 v68, v70, v68, 1.0
	v_pk_fma_f32 v[158:159], v[52:53], v[68:69], v[158:159]
	s_waitcnt vmcnt(30)
;   __device__ __forceinline__ const float* x() const { return (const float*)(const __attribute__((address_space(1))) float*)kp[0]; }
; __device__ __forceinline__ float sigmoidf_(float x) { return 1.f / (1.f + __expf(-x)); }
; __device__ __forceinline__ void phase_merge(const KP& p, char* smem, int* q, int xcc) {
;     ...
;           [&](int mi, int ni, int r, int row, int col, float v) {
;             const float gz = (float)G[(size_t)row * NU + col];
;             tot[mi][ni][r] += sigmoidf_(gz) * v;
	v_cvt_f32_f16_e32 v68, v196
	v_cvt_f32_f16_e32 v69, v197
	v_add_u32_e32 v96, 0x91000, v94
	global_load_ushort v196, v96, s[40:41] nt
	v_add_u32_e32 v96, 0x94a00, v94
	global_load_ushort v197, v96, s[40:41] nt
	v_mul_f32_e32 v68, 0xbfb8aa3b, v68
	v_mul_f32_e32 v69, 0xbfb8aa3b, v69
	v_exp_f32_e32 v68, v68
	v_exp_f32_e32 v69, v69
	s_nop 0
	v_pk_add_f32 v[68:69], v[68:69], 1.0 op_sel_hi:[1,0]
	s_nop 0
	v_div_scale_f32 v70, s[2:3], v69, v69, 1.0
	v_rcp_f32_e32 v71, v70
	s_nop 0
	v_fma_f32 v72, -v70, v71, 1.0
	v_fmac_f32_e32 v71, v72, v71
	v_div_scale_f32 v72, vcc, 1.0, v69, 1.0
	v_mul_f32_e32 v73, v72, v71
	v_fma_f32 v74, -v70, v73, v72
	v_fmac_f32_e32 v73, v74, v71
	v_fma_f32 v70, -v70, v73, v72
	v_div_fmas_f32 v70, v70, v71, v73
	v_div_fixup_f32 v69, v70, v69, 1.0
	v_div_scale_f32 v70, s[2:3], v68, v68, 1.0
	v_rcp_f32_e32 v71, v70
	s_nop 0
	v_fma_f32 v72, -v70, v71, 1.0
	v_fmac_f32_e32 v71, v72, v71
	v_div_scale_f32 v72, vcc, 1.0, v68, 1.0
	v_mul_f32_e32 v73, v72, v71
	v_fma_f32 v74, -v70, v73, v72
	v_fmac_f32_e32 v73, v74, v71
	v_fma_f32 v70, -v70, v73, v72
	v_div_fmas_f32 v70, v70, v71, v73
	v_div_fixup_f32 v68, v70, v68, 1.0
	v_pk_fma_f32 v[156:157], v[54:55], v[68:69], v[156:157]
	s_waitcnt vmcnt(30)
	v_cvt_f32_f16_e32 v68, v198
	v_cvt_f32_f16_e32 v69, v199
	v_add_u32_e32 v96, 0x98400, v94
	global_load_ushort v198, v96, s[40:41] nt
	v_add_u32_e32 v96, 0x9be00, v94
	global_load_ushort v199, v96, s[40:41] nt
	v_mul_f32_e32 v68, 0xbfb8aa3b, v68
	v_mul_f32_e32 v69, 0xbfb8aa3b, v69
	v_exp_f32_e32 v68, v68
	v_exp_f32_e32 v69, v69
	s_nop 0
	v_pk_add_f32 v[68:69], v[68:69], 1.0 op_sel_hi:[1,0]
	s_nop 0
	v_div_scale_f32 v70, s[2:3], v69, v69, 1.0
	v_rcp_f32_e32 v71, v70
	s_nop 0
	v_fma_f32 v72, -v70, v71, 1.0
	v_fmac_f32_e32 v71, v72, v71
	v_div_scale_f32 v72, vcc, 1.0, v69, 1.0
	v_mul_f32_e32 v73, v72, v71
	v_fma_f32 v74, -v70, v73, v72
	v_fmac_f32_e32 v73, v74, v71
	v_fma_f32 v70, -v70, v73, v72
	v_div_fmas_f32 v70, v70, v71, v73
	v_div_fixup_f32 v69, v70, v69, 1.0
	v_div_scale_f32 v70, s[2:3], v68, v68, 1.0
	v_rcp_f32_e32 v71, v70
	s_nop 0
	v_fma_f32 v72, -v70, v71, 1.0
	v_fmac_f32_e32 v71, v72, v71
	v_div_scale_f32 v72, vcc, 1.0, v68, 1.0
	v_mul_f32_e32 v73, v72, v71
	v_fma_f32 v74, -v70, v73, v72
	v_fmac_f32_e32 v73, v74, v71
	v_fma_f32 v70, -v70, v73, v72
	v_div_fmas_f32 v70, v70, v71, v73
	v_div_fixup_f32 v68, v70, v68, 1.0
	v_pk_fma_f32 v[154:155], v[56:57], v[68:69], v[154:155]
	s_waitcnt vmcnt(30)
	v_cvt_f32_f16_e32 v68, v200
	v_cvt_f32_f16_e32 v69, v201
	v_add_u32_e32 v96, 0xae000, v94
	global_load_ushort v200, v96, s[40:41] nt
	v_add_u32_e32 v96, 0xb1a00, v94
	global_load_ushort v201, v96, s[40:41] nt
	v_mul_f32_e32 v68, 0xbfb8aa3b, v68
	v_mul_f32_e32 v69, 0xbfb8aa3b, v69
	v_exp_f32_e32 v68, v68
	v_exp_f32_e32 v69, v69
	s_nop 0
	v_pk_add_f32 v[68:69], v[68:69], 1.0 op_sel_hi:[1,0]
	s_nop 0
	v_div_scale_f32 v70, s[2:3], v69, v69, 1.0
	v_rcp_f32_e32 v71, v70
	s_nop 0
	v_fma_f32 v72, -v70, v71, 1.0
	v_fmac_f32_e32 v71, v72, v71
	v_div_scale_f32 v72, vcc, 1.0, v69, 1.0
	v_mul_f32_e32 v73, v72, v71
	v_fma_f32 v74, -v70, v73, v72
	v_fmac_f32_e32 v73, v74, v71
	v_fma_f32 v70, -v70, v73, v72
	v_div_fmas_f32 v70, v70, v71, v73
	v_div_fixup_f32 v69, v70, v69, 1.0
	v_div_scale_f32 v70, s[2:3], v68, v68, 1.0
	v_rcp_f32_e32 v71, v70
	s_nop 0
	v_fma_f32 v72, -v70, v71, 1.0
	v_fmac_f32_e32 v71, v72, v71
	v_div_scale_f32 v72, vcc, 1.0, v68, 1.0
	v_mul_f32_e32 v73, v72, v71
	v_fma_f32 v74, -v70, v73, v72
	v_fmac_f32_e32 v73, v74, v71
	v_fma_f32 v70, -v70, v73, v72
	v_div_fmas_f32 v70, v70, v71, v73
	v_div_fixup_f32 v68, v70, v68, 1.0
	v_pk_fma_f32 v[152:153], v[58:59], v[68:69], v[152:153]
	s_waitcnt vmcnt(30)
	v_cvt_f32_f16_e32 v68, v202
	v_cvt_f32_f16_e32 v69, v203
	v_add_u32_e32 v96, 0xb5400, v94
	global_load_ushort v202, v96, s[40:41] nt
	v_add_u32_e32 v96, 0xb8e00, v94
	global_load_ushort v203, v96, s[40:41] nt
	v_mul_f32_e32 v68, 0xbfb8aa3b, v68
	v_mul_f32_e32 v69, 0xbfb8aa3b, v69
	v_exp_f32_e32 v68, v68
	v_exp_f32_e32 v69, v69
	s_nop 0
	v_pk_add_f32 v[68:69], v[68:69], 1.0 op_sel_hi:[1,0]
	s_nop 0
	v_div_scale_f32 v70, s[2:3], v69, v69, 1.0
	v_rcp_f32_e32 v71, v70
	s_nop 0
	v_fma_f32 v72, -v70, v71, 1.0
	v_fmac_f32_e32 v71, v72, v71
	v_div_scale_f32 v72, vcc, 1.0, v69, 1.0
	v_mul_f32_e32 v73, v72, v71
	v_fma_f32 v74, -v70, v73, v72
	v_fmac_f32_e32 v73, v74, v71
	v_fma_f32 v70, -v70, v73, v72
	v_div_fmas_f32 v70, v70, v71, v73
	v_div_fixup_f32 v69, v70, v69, 1.0
	v_div_scale_f32 v70, s[2:3], v68, v68, 1.0
	v_rcp_f32_e32 v71, v70
	s_nop 0
	v_fma_f32 v72, -v70, v71, 1.0
	v_fmac_f32_e32 v71, v72, v71
	v_div_scale_f32 v72, vcc, 1.0, v68, 1.0
	v_mul_f32_e32 v73, v72, v71
	v_fma_f32 v74, -v70, v73, v72
	v_fmac_f32_e32 v73, v74, v71
	v_fma_f32 v70, -v70, v73, v72
	v_div_fmas_f32 v70, v70, v71, v73
	v_div_fixup_f32 v68, v70, v68, 1.0
	v_pk_fma_f32 v[150:151], v[60:61], v[68:69], v[150:151]
	s_waitcnt vmcnt(30)
	v_cvt_f32_f16_e32 v68, v204
	v_cvt_f32_f16_e32 v69, v205
	v_add_u32_e32 v96, 0xcb000, v94
	global_load_ushort v204, v96, s[40:41] nt
	v_add_u32_e32 v96, 0xcea00, v94
	global_load_ushort v205, v96, s[40:41] nt
	v_mul_f32_e32 v68, 0xbfb8aa3b, v68
	v_mul_f32_e32 v69, 0xbfb8aa3b, v69
	v_exp_f32_e32 v68, v68
	v_exp_f32_e32 v69, v69
	s_nop 0
	v_pk_add_f32 v[68:69], v[68:69], 1.0 op_sel_hi:[1,0]
	s_nop 0
	v_div_scale_f32 v70, s[2:3], v69, v69, 1.0
	v_rcp_f32_e32 v71, v70
	s_nop 0
	v_fma_f32 v72, -v70, v71, 1.0
	v_fmac_f32_e32 v71, v72, v71
	v_div_scale_f32 v72, vcc, 1.0, v69, 1.0
	v_mul_f32_e32 v73, v72, v71
	v_fma_f32 v74, -v70, v73, v72
	v_fmac_f32_e32 v73, v74, v71
	v_fma_f32 v70, -v70, v73, v72
	v_div_fmas_f32 v70, v70, v71, v73
	v_div_fixup_f32 v69, v70, v69, 1.0
	v_div_scale_f32 v70, s[2:3], v68, v68, 1.0
	v_rcp_f32_e32 v71, v70
	s_nop 0
	v_fma_f32 v72, -v70, v71, 1.0
	v_fmac_f32_e32 v71, v72, v71
	v_div_scale_f32 v72, vcc, 1.0, v68, 1.0
	v_mul_f32_e32 v73, v72, v71
	v_fma_f32 v74, -v70, v73, v72
	v_fmac_f32_e32 v73, v74, v71
	v_fma_f32 v70, -v70, v73, v72
	v_div_fmas_f32 v70, v70, v71, v73
	v_div_fixup_f32 v68, v70, v68, 1.0
	v_pk_fma_f32 v[148:149], v[62:63], v[68:69], v[148:149]
	s_waitcnt vmcnt(30)
;   __device__ __forceinline__ const float* x() const { return (const float*)(const __attribute__((address_space(1))) float*)kp[0]; }
; __device__ __forceinline__ float sigmoidf_(float x) { return 1.f / (1.f + __expf(-x)); }
; __device__ __forceinline__ void phase_merge(const KP& p, char* smem, int* q, int xcc) {
;     ...
;           [&](int mi, int ni, int r, int row, int col, float v) {
;             const float gz = (float)G[(size_t)row * NU + col];
;             tot[mi][ni][r] += sigmoidf_(gz) * v;
	v_cvt_f32_f16_e32 v68, v206
	v_cvt_f32_f16_e32 v69, v207
	v_add_u32_e32 v96, 0xd2400, v94
	global_load_ushort v206, v96, s[40:41] nt
	v_add_u32_e32 v96, 0xd5e00, v94
	global_load_ushort v207, v96, s[40:41] nt
	v_mul_f32_e32 v68, 0xbfb8aa3b, v68
	v_mul_f32_e32 v69, 0xbfb8aa3b, v69
	v_exp_f32_e32 v68, v68
	v_exp_f32_e32 v69, v69
	s_nop 0
	v_pk_add_f32 v[68:69], v[68:69], 1.0 op_sel_hi:[1,0]
	s_nop 0
	v_div_scale_f32 v70, s[2:3], v69, v69, 1.0
	v_rcp_f32_e32 v71, v70
	s_nop 0
	v_fma_f32 v72, -v70, v71, 1.0
	v_fmac_f32_e32 v71, v72, v71
	v_div_scale_f32 v72, vcc, 1.0, v69, 1.0
	v_mul_f32_e32 v73, v72, v71
	v_fma_f32 v74, -v70, v73, v72
	v_fmac_f32_e32 v73, v74, v71
	v_fma_f32 v70, -v70, v73, v72
	v_div_fmas_f32 v70, v70, v71, v73
	v_div_fixup_f32 v69, v70, v69, 1.0
	v_div_scale_f32 v70, s[2:3], v68, v68, 1.0
	v_rcp_f32_e32 v71, v70
	s_nop 0
	v_fma_f32 v72, -v70, v71, 1.0
	v_fmac_f32_e32 v71, v72, v71
	v_div_scale_f32 v72, vcc, 1.0, v68, 1.0
	v_mul_f32_e32 v73, v72, v71
	v_fma_f32 v74, -v70, v73, v72
	v_fmac_f32_e32 v73, v74, v71
	v_fma_f32 v70, -v70, v73, v72
	v_div_fmas_f32 v70, v70, v71, v73
	v_div_fixup_f32 v68, v70, v68, 1.0
	v_pk_fma_f32 v[146:147], v[64:65], v[68:69], v[146:147]
	s_waitcnt vmcnt(30)
	v_cvt_f32_f16_e32 v68, v208
	v_cvt_f32_f16_e32 v69, v209
	v_add_u32_e32 v96, 0x74000, v94
	global_load_ushort v208, v96, s[40:41] offset:64 nt
	v_add_u32_e32 v96, 0x77a00, v94
	global_load_ushort v209, v96, s[40:41] offset:64 nt
	v_mul_f32_e32 v68, 0xbfb8aa3b, v68
	v_mul_f32_e32 v69, 0xbfb8aa3b, v69
	v_exp_f32_e32 v68, v68
	v_exp_f32_e32 v69, v69
	s_nop 0
	v_pk_add_f32 v[68:69], v[68:69], 1.0 op_sel_hi:[1,0]
	s_nop 0
	v_div_scale_f32 v70, s[2:3], v69, v69, 1.0
	v_rcp_f32_e32 v71, v70
	s_nop 0
	v_fma_f32 v72, -v70, v71, 1.0
	v_fmac_f32_e32 v71, v72, v71
	v_div_scale_f32 v72, vcc, 1.0, v69, 1.0
	v_mul_f32_e32 v73, v72, v71
	v_fma_f32 v74, -v70, v73, v72
	v_fmac_f32_e32 v73, v74, v71
	v_fma_f32 v70, -v70, v73, v72
	v_div_fmas_f32 v70, v70, v71, v73
	v_div_fixup_f32 v69, v70, v69, 1.0
	v_div_scale_f32 v70, s[2:3], v68, v68, 1.0
	v_rcp_f32_e32 v71, v70
	s_nop 0
	v_fma_f32 v72, -v70, v71, 1.0
	v_fmac_f32_e32 v71, v72, v71
	v_div_scale_f32 v72, vcc, 1.0, v68, 1.0
	v_mul_f32_e32 v73, v72, v71
	v_fma_f32 v74, -v70, v73, v72
	v_fmac_f32_e32 v73, v74, v71
	v_fma_f32 v70, -v70, v73, v72
	v_div_fmas_f32 v70, v70, v71, v73
	v_div_fixup_f32 v68, v70, v68, 1.0
	v_pk_fma_f32 v[144:145], v[34:35], v[68:69], v[144:145]
	s_waitcnt vmcnt(30)
	v_cvt_f32_f16_e32 v68, v210
	v_cvt_f32_f16_e32 v69, v211
	v_add_u32_e32 v96, 0x7b400, v94
	global_load_ushort v210, v96, s[40:41] offset:64 nt
	v_add_u32_e32 v96, 0x7ee00, v94
	global_load_ushort v211, v96, s[40:41] offset:64 nt
	v_mul_f32_e32 v68, 0xbfb8aa3b, v68
	v_mul_f32_e32 v69, 0xbfb8aa3b, v69
	v_exp_f32_e32 v68, v68
	v_exp_f32_e32 v69, v69
	s_nop 0
	v_pk_add_f32 v[68:69], v[68:69], 1.0 op_sel_hi:[1,0]
	s_nop 0
	v_div_scale_f32 v70, s[2:3], v69, v69, 1.0
	v_rcp_f32_e32 v71, v70
	s_nop 0
	v_fma_f32 v72, -v70, v71, 1.0
	v_fmac_f32_e32 v71, v72, v71
	v_div_scale_f32 v72, vcc, 1.0, v69, 1.0
	v_mul_f32_e32 v73, v72, v71
	v_fma_f32 v74, -v70, v73, v72
	v_fmac_f32_e32 v73, v74, v71
	v_fma_f32 v70, -v70, v73, v72
	v_div_fmas_f32 v70, v70, v71, v73
	v_div_fixup_f32 v69, v70, v69, 1.0
	v_div_scale_f32 v70, s[2:3], v68, v68, 1.0
	v_rcp_f32_e32 v71, v70
	s_nop 0
	v_fma_f32 v72, -v70, v71, 1.0
	v_fmac_f32_e32 v71, v72, v71
	v_div_scale_f32 v72, vcc, 1.0, v68, 1.0
	v_mul_f32_e32 v73, v72, v71
	v_fma_f32 v74, -v70, v73, v72
	v_fmac_f32_e32 v73, v74, v71
	v_fma_f32 v70, -v70, v73, v72
	v_div_fmas_f32 v70, v70, v71, v73
	v_div_fixup_f32 v68, v70, v68, 1.0
	v_pk_fma_f32 v[142:143], v[36:37], v[68:69], v[142:143]
	s_waitcnt vmcnt(30)
	v_cvt_f32_f16_e32 v68, v212
	v_cvt_f32_f16_e32 v69, v213
	v_add_u32_e32 v96, 0x91000, v94
	global_load_ushort v212, v96, s[40:41] offset:64 nt
	v_add_u32_e32 v96, 0x94a00, v94
	global_load_ushort v213, v96, s[40:41] offset:64 nt
	v_mul_f32_e32 v68, 0xbfb8aa3b, v68
	v_mul_f32_e32 v69, 0xbfb8aa3b, v69
	v_exp_f32_e32 v68, v68
	v_exp_f32_e32 v69, v69
	s_nop 0
	v_pk_add_f32 v[68:69], v[68:69], 1.0 op_sel_hi:[1,0]
	s_nop 0
	v_div_scale_f32 v70, s[2:3], v69, v69, 1.0
	v_rcp_f32_e32 v71, v70
	s_nop 0
	v_fma_f32 v72, -v70, v71, 1.0
	v_fmac_f32_e32 v71, v72, v71
	v_div_scale_f32 v72, vcc, 1.0, v69, 1.0
	v_mul_f32_e32 v73, v72, v71
	v_fma_f32 v74, -v70, v73, v72
	v_fmac_f32_e32 v73, v74, v71
	v_fma_f32 v70, -v70, v73, v72
	v_div_fmas_f32 v70, v70, v71, v73
	v_div_fixup_f32 v69, v70, v69, 1.0
	v_div_scale_f32 v70, s[2:3], v68, v68, 1.0
	v_rcp_f32_e32 v71, v70
	s_nop 0
	v_fma_f32 v72, -v70, v71, 1.0
	v_fmac_f32_e32 v71, v72, v71
	v_div_scale_f32 v72, vcc, 1.0, v68, 1.0
	v_mul_f32_e32 v73, v72, v71
	v_fma_f32 v74, -v70, v73, v72
	v_fmac_f32_e32 v73, v74, v71
	v_fma_f32 v70, -v70, v73, v72
	v_div_fmas_f32 v70, v70, v71, v73
	v_div_fixup_f32 v68, v70, v68, 1.0
	v_pk_fma_f32 v[140:141], v[38:39], v[68:69], v[140:141]
	s_waitcnt vmcnt(30)
	v_cvt_f32_f16_e32 v68, v214
	v_cvt_f32_f16_e32 v69, v215
	v_add_u32_e32 v96, 0x98400, v94
	global_load_ushort v214, v96, s[40:41] offset:64 nt
	v_add_u32_e32 v96, 0x9be00, v94
	global_load_ushort v215, v96, s[40:41] offset:64 nt
	v_mul_f32_e32 v68, 0xbfb8aa3b, v68
	v_mul_f32_e32 v69, 0xbfb8aa3b, v69
	v_exp_f32_e32 v68, v68
	v_exp_f32_e32 v69, v69
	s_nop 0
	v_pk_add_f32 v[68:69], v[68:69], 1.0 op_sel_hi:[1,0]
	s_nop 0
	v_div_scale_f32 v70, s[2:3], v69, v69, 1.0
	v_rcp_f32_e32 v71, v70
	s_nop 0
	v_fma_f32 v72, -v70, v71, 1.0
	v_fmac_f32_e32 v71, v72, v71
	v_div_scale_f32 v72, vcc, 1.0, v69, 1.0
	v_mul_f32_e32 v73, v72, v71
	v_fma_f32 v74, -v70, v73, v72
	v_fmac_f32_e32 v73, v74, v71
	v_fma_f32 v70, -v70, v73, v72
	v_div_fmas_f32 v70, v70, v71, v73
	v_div_fixup_f32 v69, v70, v69, 1.0
	v_div_scale_f32 v70, s[2:3], v68, v68, 1.0
	v_rcp_f32_e32 v71, v70
	s_nop 0
	v_fma_f32 v72, -v70, v71, 1.0
	v_fmac_f32_e32 v71, v72, v71
	v_div_scale_f32 v72, vcc, 1.0, v68, 1.0
	v_mul_f32_e32 v73, v72, v71
	v_fma_f32 v74, -v70, v73, v72
	v_fmac_f32_e32 v73, v74, v71
	v_fma_f32 v70, -v70, v73, v72
	v_div_fmas_f32 v70, v70, v71, v73
	v_div_fixup_f32 v68, v70, v68, 1.0
	v_pk_fma_f32 v[138:139], v[40:41], v[68:69], v[138:139]
	s_waitcnt vmcnt(30)
;   __device__ __forceinline__ const float* x() const { return (const float*)(const __attribute__((address_space(1))) float*)kp[0]; }
; __device__ __forceinline__ float sigmoidf_(float x) { return 1.f / (1.f + __expf(-x)); }
; __device__ __forceinline__ void phase_merge(const KP& p, char* smem, int* q, int xcc) {
;     ...
;           [&](int mi, int ni, int r, int row, int col, float v) {
;             const float gz = (float)G[(size_t)row * NU + col];
;             tot[mi][ni][r] += sigmoidf_(gz) * v;
	v_cvt_f32_f16_e32 v68, v216
	v_cvt_f32_f16_e32 v69, v217
	v_add_u32_e32 v96, 0xae000, v94
	global_load_ushort v216, v96, s[40:41] offset:64 nt
	v_add_u32_e32 v96, 0xb1a00, v94
	global_load_ushort v217, v96, s[40:41] offset:64 nt
	v_mul_f32_e32 v68, 0xbfb8aa3b, v68
	v_mul_f32_e32 v69, 0xbfb8aa3b, v69
	v_exp_f32_e32 v68, v68
	v_exp_f32_e32 v69, v69
	s_nop 0
	v_pk_add_f32 v[68:69], v[68:69], 1.0 op_sel_hi:[1,0]
	s_nop 0
	v_div_scale_f32 v70, s[2:3], v69, v69, 1.0
	v_rcp_f32_e32 v71, v70
	s_nop 0
	v_fma_f32 v72, -v70, v71, 1.0
	v_fmac_f32_e32 v71, v72, v71
	v_div_scale_f32 v72, vcc, 1.0, v69, 1.0
	v_mul_f32_e32 v73, v72, v71
	v_fma_f32 v74, -v70, v73, v72
	v_fmac_f32_e32 v73, v74, v71
	v_fma_f32 v70, -v70, v73, v72
	v_div_fmas_f32 v70, v70, v71, v73
	v_div_fixup_f32 v69, v70, v69, 1.0
	v_div_scale_f32 v70, s[2:3], v68, v68, 1.0
	v_rcp_f32_e32 v71, v70
	s_nop 0
	v_fma_f32 v72, -v70, v71, 1.0
	v_fmac_f32_e32 v71, v72, v71
	v_div_scale_f32 v72, vcc, 1.0, v68, 1.0
	v_mul_f32_e32 v73, v72, v71
	v_fma_f32 v74, -v70, v73, v72
	v_fmac_f32_e32 v73, v74, v71
	v_fma_f32 v70, -v70, v73, v72
	v_div_fmas_f32 v70, v70, v71, v73
	v_div_fixup_f32 v68, v70, v68, 1.0
	v_pk_fma_f32 v[136:137], v[42:43], v[68:69], v[136:137]
	s_waitcnt vmcnt(30)
	v_cvt_f32_f16_e32 v68, v218
	v_cvt_f32_f16_e32 v69, v219
	v_add_u32_e32 v96, 0xb5400, v94
	global_load_ushort v218, v96, s[40:41] offset:64 nt
	v_add_u32_e32 v96, 0xb8e00, v94
	global_load_ushort v219, v96, s[40:41] offset:64 nt
	v_mul_f32_e32 v68, 0xbfb8aa3b, v68
	v_mul_f32_e32 v69, 0xbfb8aa3b, v69
	v_exp_f32_e32 v68, v68
	v_exp_f32_e32 v69, v69
	s_nop 0
	v_pk_add_f32 v[68:69], v[68:69], 1.0 op_sel_hi:[1,0]
	s_nop 0
	v_div_scale_f32 v70, s[2:3], v69, v69, 1.0
	v_rcp_f32_e32 v71, v70
	s_nop 0
	v_fma_f32 v72, -v70, v71, 1.0
	v_fmac_f32_e32 v71, v72, v71
	v_div_scale_f32 v72, vcc, 1.0, v69, 1.0
	v_mul_f32_e32 v73, v72, v71
	v_fma_f32 v74, -v70, v73, v72
	v_fmac_f32_e32 v73, v74, v71
	v_fma_f32 v70, -v70, v73, v72
	v_div_fmas_f32 v70, v70, v71, v73
	v_div_fixup_f32 v69, v70, v69, 1.0
	v_div_scale_f32 v70, s[2:3], v68, v68, 1.0
	v_rcp_f32_e32 v71, v70
	s_nop 0
	v_fma_f32 v72, -v70, v71, 1.0
	v_fmac_f32_e32 v71, v72, v71
	v_div_scale_f32 v72, vcc, 1.0, v68, 1.0
	v_mul_f32_e32 v73, v72, v71
	v_fma_f32 v74, -v70, v73, v72
	v_fmac_f32_e32 v73, v74, v71
	v_fma_f32 v70, -v70, v73, v72
	v_div_fmas_f32 v70, v70, v71, v73
	v_div_fixup_f32 v68, v70, v68, 1.0
	v_pk_fma_f32 v[134:135], v[44:45], v[68:69], v[134:135]
	s_waitcnt vmcnt(30)
	v_cvt_f32_f16_e32 v68, v220
	v_cvt_f32_f16_e32 v69, v221
	v_add_u32_e32 v96, 0xcb000, v94
	global_load_ushort v220, v96, s[40:41] offset:64 nt
	v_add_u32_e32 v96, 0xcea00, v94
	global_load_ushort v221, v96, s[40:41] offset:64 nt
	v_mul_f32_e32 v68, 0xbfb8aa3b, v68
	v_mul_f32_e32 v69, 0xbfb8aa3b, v69
	v_exp_f32_e32 v68, v68
	v_exp_f32_e32 v69, v69
	s_nop 0
	v_pk_add_f32 v[68:69], v[68:69], 1.0 op_sel_hi:[1,0]
	s_nop 0
	v_div_scale_f32 v70, s[2:3], v69, v69, 1.0
	v_rcp_f32_e32 v71, v70
	s_nop 0
	v_fma_f32 v72, -v70, v71, 1.0
	v_fmac_f32_e32 v71, v72, v71
	v_div_scale_f32 v72, vcc, 1.0, v69, 1.0
	v_mul_f32_e32 v73, v72, v71
	v_fma_f32 v74, -v70, v73, v72
	v_fmac_f32_e32 v73, v74, v71
	v_fma_f32 v70, -v70, v73, v72
	v_div_fmas_f32 v70, v70, v71, v73
	v_div_fixup_f32 v69, v70, v69, 1.0
	v_div_scale_f32 v70, s[2:3], v68, v68, 1.0
	v_rcp_f32_e32 v71, v70
	s_nop 0
	v_fma_f32 v72, -v70, v71, 1.0
	v_fmac_f32_e32 v71, v72, v71
	v_div_scale_f32 v72, vcc, 1.0, v68, 1.0
	v_mul_f32_e32 v73, v72, v71
	v_fma_f32 v74, -v70, v73, v72
	v_fmac_f32_e32 v73, v74, v71
	v_fma_f32 v70, -v70, v73, v72
	v_div_fmas_f32 v70, v70, v71, v73
	v_div_fixup_f32 v68, v70, v68, 1.0
	v_pk_fma_f32 v[132:133], v[46:47], v[68:69], v[132:133]
	s_waitcnt vmcnt(30)
	v_cvt_f32_f16_e32 v68, v222
	v_cvt_f32_f16_e32 v69, v223
	v_add_u32_e32 v96, 0xd2400, v94
	global_load_ushort v222, v96, s[40:41] offset:64 nt
	v_add_u32_e32 v96, 0xd5e00, v94
	global_load_ushort v223, v96, s[40:41] offset:64 nt
	v_mul_f32_e32 v68, 0xbfb8aa3b, v68
	v_mul_f32_e32 v69, 0xbfb8aa3b, v69
	v_exp_f32_e32 v68, v68
	v_exp_f32_e32 v69, v69
	s_nop 0
	v_pk_add_f32 v[68:69], v[68:69], 1.0 op_sel_hi:[1,0]
	s_nop 0
	v_div_scale_f32 v70, s[2:3], v69, v69, 1.0
	v_rcp_f32_e32 v71, v70
	s_nop 0
	v_fma_f32 v72, -v70, v71, 1.0
	v_fmac_f32_e32 v71, v72, v71
	v_div_scale_f32 v72, vcc, 1.0, v69, 1.0
	v_mul_f32_e32 v73, v72, v71
	v_fma_f32 v74, -v70, v73, v72
	v_fmac_f32_e32 v73, v74, v71
	v_fma_f32 v70, -v70, v73, v72
	v_div_fmas_f32 v70, v70, v71, v73
	v_div_fixup_f32 v69, v70, v69, 1.0
	v_div_scale_f32 v70, s[2:3], v68, v68, 1.0
	v_rcp_f32_e32 v71, v70
	s_nop 0
	v_fma_f32 v72, -v70, v71, 1.0
	v_fmac_f32_e32 v71, v72, v71
	v_div_scale_f32 v72, vcc, 1.0, v68, 1.0
	v_mul_f32_e32 v73, v72, v71
	v_fma_f32 v74, -v70, v73, v72
	v_fmac_f32_e32 v73, v74, v71
	v_fma_f32 v70, -v70, v73, v72
	v_div_fmas_f32 v70, v70, v71, v73
	v_div_fixup_f32 v68, v70, v68, 1.0
	v_pk_fma_f32 v[130:131], v[48:49], v[68:69], v[130:131]
	s_waitcnt vmcnt(30)
	v_cvt_f32_f16_e32 v68, v192
	v_cvt_f32_f16_e32 v69, v193
	v_mul_f32_e32 v68, 0xbfb8aa3b, v68
	v_mul_f32_e32 v69, 0xbfb8aa3b, v69
	v_exp_f32_e32 v68, v68
	v_exp_f32_e32 v69, v69
	s_nop 0
	v_pk_add_f32 v[68:69], v[68:69], 1.0 op_sel_hi:[1,0]
	s_nop 0
	v_div_scale_f32 v70, s[2:3], v69, v69, 1.0
	v_rcp_f32_e32 v71, v70
	s_nop 0
	v_fma_f32 v72, -v70, v71, 1.0
	v_fmac_f32_e32 v71, v72, v71
	v_div_scale_f32 v72, vcc, 1.0, v69, 1.0
	v_mul_f32_e32 v73, v72, v71
	v_fma_f32 v74, -v70, v73, v72
	v_fmac_f32_e32 v73, v74, v71
	v_fma_f32 v70, -v70, v73, v72
	v_div_fmas_f32 v70, v70, v71, v73
	v_div_fixup_f32 v69, v70, v69, 1.0
	v_div_scale_f32 v70, s[2:3], v68, v68, 1.0
	v_rcp_f32_e32 v71, v70
	s_nop 0
	v_fma_f32 v72, -v70, v71, 1.0
	v_fmac_f32_e32 v71, v72, v71
	v_div_scale_f32 v72, vcc, 1.0, v68, 1.0
	v_mul_f32_e32 v73, v72, v71
	v_fma_f32 v74, -v70, v73, v72
	v_fmac_f32_e32 v73, v74, v71
	v_fma_f32 v70, -v70, v73, v72
	v_div_fmas_f32 v70, v70, v71, v73
	v_div_fixup_f32 v68, v70, v68, 1.0
	v_pk_fma_f32 v[128:129], v[18:19], v[68:69], v[128:129]
	s_waitcnt vmcnt(28)
;   __device__ __forceinline__ const float* x() const { return (const float*)(const __attribute__((address_space(1))) float*)kp[0]; }
; __device__ __forceinline__ float sigmoidf_(float x) { return 1.f / (1.f + __expf(-x)); }
; __device__ __forceinline__ void phase_merge(const KP& p, char* smem, int* q, int xcc) {
;     ...
;           [&](int mi, int ni, int r, int row, int col, float v) {
;             const float gz = (float)G[(size_t)row * NU + col];
;             tot[mi][ni][r] += sigmoidf_(gz) * v;
	v_cvt_f32_f16_e32 v68, v194
	v_cvt_f32_f16_e32 v69, v195
	v_mul_f32_e32 v68, 0xbfb8aa3b, v68
	v_mul_f32_e32 v69, 0xbfb8aa3b, v69
	v_exp_f32_e32 v68, v68
	v_exp_f32_e32 v69, v69
	s_nop 0
	v_pk_add_f32 v[68:69], v[68:69], 1.0 op_sel_hi:[1,0]
	s_nop 0
	v_div_scale_f32 v70, s[2:3], v69, v69, 1.0
	v_rcp_f32_e32 v71, v70
	s_nop 0
	v_fma_f32 v72, -v70, v71, 1.0
	v_fmac_f32_e32 v71, v72, v71
	v_div_scale_f32 v72, vcc, 1.0, v69, 1.0
	v_mul_f32_e32 v73, v72, v71
	v_fma_f32 v74, -v70, v73, v72
	v_fmac_f32_e32 v73, v74, v71
	v_fma_f32 v70, -v70, v73, v72
	v_div_fmas_f32 v70, v70, v71, v73
	v_div_fixup_f32 v69, v70, v69, 1.0
	v_div_scale_f32 v70, s[2:3], v68, v68, 1.0
	v_rcp_f32_e32 v71, v70
	s_nop 0
	v_fma_f32 v72, -v70, v71, 1.0
	v_fmac_f32_e32 v71, v72, v71
	v_div_scale_f32 v72, vcc, 1.0, v68, 1.0
	v_mul_f32_e32 v73, v72, v71
	v_fma_f32 v74, -v70, v73, v72
	v_fmac_f32_e32 v73, v74, v71
	v_fma_f32 v70, -v70, v73, v72
	v_div_fmas_f32 v70, v70, v71, v73
	v_div_fixup_f32 v68, v70, v68, 1.0
	v_pk_fma_f32 v[126:127], v[20:21], v[68:69], v[126:127]
	s_waitcnt vmcnt(26)
	v_cvt_f32_f16_e32 v68, v196
	v_cvt_f32_f16_e32 v69, v197
	v_mul_f32_e32 v68, 0xbfb8aa3b, v68
	v_mul_f32_e32 v69, 0xbfb8aa3b, v69
	v_exp_f32_e32 v68, v68
	v_exp_f32_e32 v69, v69
	s_nop 0
	v_pk_add_f32 v[68:69], v[68:69], 1.0 op_sel_hi:[1,0]
	s_nop 0
	v_div_scale_f32 v70, s[2:3], v69, v69, 1.0
	v_rcp_f32_e32 v71, v70
	s_nop 0
	v_fma_f32 v72, -v70, v71, 1.0
	v_fmac_f32_e32 v71, v72, v71
	v_div_scale_f32 v72, vcc, 1.0, v69, 1.0
	v_mul_f32_e32 v73, v72, v71
	v_fma_f32 v74, -v70, v73, v72
	v_fmac_f32_e32 v73, v74, v71
	v_fma_f32 v70, -v70, v73, v72
	v_div_fmas_f32 v70, v70, v71, v73
	v_div_fixup_f32 v69, v70, v69, 1.0
	v_div_scale_f32 v70, s[2:3], v68, v68, 1.0
	v_rcp_f32_e32 v71, v70
	s_nop 0
	v_fma_f32 v72, -v70, v71, 1.0
	v_fmac_f32_e32 v71, v72, v71
	v_div_scale_f32 v72, vcc, 1.0, v68, 1.0
	v_mul_f32_e32 v73, v72, v71
	v_fma_f32 v74, -v70, v73, v72
	v_fmac_f32_e32 v73, v74, v71
	v_fma_f32 v70, -v70, v73, v72
	v_div_fmas_f32 v70, v70, v71, v73
	v_div_fixup_f32 v68, v70, v68, 1.0
	v_pk_fma_f32 v[124:125], v[22:23], v[68:69], v[124:125]
	s_waitcnt vmcnt(24)
	v_cvt_f32_f16_e32 v68, v198
	v_cvt_f32_f16_e32 v69, v199
	v_mul_f32_e32 v68, 0xbfb8aa3b, v68
	v_mul_f32_e32 v69, 0xbfb8aa3b, v69
	v_exp_f32_e32 v68, v68
	v_exp_f32_e32 v69, v69
	s_nop 0
	v_pk_add_f32 v[68:69], v[68:69], 1.0 op_sel_hi:[1,0]
	s_nop 0
	v_div_scale_f32 v70, s[2:3], v69, v69, 1.0
	v_rcp_f32_e32 v71, v70
	s_nop 0
	v_fma_f32 v72, -v70, v71, 1.0
	v_fmac_f32_e32 v71, v72, v71
	v_div_scale_f32 v72, vcc, 1.0, v69, 1.0
	v_mul_f32_e32 v73, v72, v71
	v_fma_f32 v74, -v70, v73, v72
	v_fmac_f32_e32 v73, v74, v71
	v_fma_f32 v70, -v70, v73, v72
	v_div_fmas_f32 v70, v70, v71, v73
	v_div_fixup_f32 v69, v70, v69, 1.0
	v_div_scale_f32 v70, s[2:3], v68, v68, 1.0
	v_rcp_f32_e32 v71, v70
	s_nop 0
	v_fma_f32 v72, -v70, v71, 1.0
	v_fmac_f32_e32 v71, v72, v71
	v_div_scale_f32 v72, vcc, 1.0, v68, 1.0
	v_mul_f32_e32 v73, v72, v71
	v_fma_f32 v74, -v70, v73, v72
	v_fmac_f32_e32 v73, v74, v71
	v_fma_f32 v70, -v70, v73, v72
	v_div_fmas_f32 v70, v70, v71, v73
	v_div_fixup_f32 v68, v70, v68, 1.0
	v_pk_fma_f32 v[122:123], v[24:25], v[68:69], v[122:123]
	s_waitcnt vmcnt(22)
	v_cvt_f32_f16_e32 v68, v200
	v_cvt_f32_f16_e32 v69, v201
	v_mul_f32_e32 v68, 0xbfb8aa3b, v68
	v_mul_f32_e32 v69, 0xbfb8aa3b, v69
	v_exp_f32_e32 v68, v68
	v_exp_f32_e32 v69, v69
	s_nop 0
	v_pk_add_f32 v[68:69], v[68:69], 1.0 op_sel_hi:[1,0]
	s_nop 0
	v_div_scale_f32 v70, s[2:3], v69, v69, 1.0
	v_rcp_f32_e32 v71, v70
	s_nop 0
	v_fma_f32 v72, -v70, v71, 1.0
	v_fmac_f32_e32 v71, v72, v71
	v_div_scale_f32 v72, vcc, 1.0, v69, 1.0
	v_mul_f32_e32 v73, v72, v71
	v_fma_f32 v74, -v70, v73, v72
	v_fmac_f32_e32 v73, v74, v71
	v_fma_f32 v70, -v70, v73, v72
	v_div_fmas_f32 v70, v70, v71, v73
	v_div_fixup_f32 v69, v70, v69, 1.0
	v_div_scale_f32 v70, s[2:3], v68, v68, 1.0
	v_rcp_f32_e32 v71, v70
	s_nop 0
	v_fma_f32 v72, -v70, v71, 1.0
	v_fmac_f32_e32 v71, v72, v71
	v_div_scale_f32 v72, vcc, 1.0, v68, 1.0
	v_mul_f32_e32 v73, v72, v71
	v_fma_f32 v74, -v70, v73, v72
	v_fmac_f32_e32 v73, v74, v71
	v_fma_f32 v70, -v70, v73, v72
	v_div_fmas_f32 v70, v70, v71, v73
	v_div_fixup_f32 v68, v70, v68, 1.0
	v_pk_fma_f32 v[120:121], v[26:27], v[68:69], v[120:121]
	s_waitcnt vmcnt(20)
	v_cvt_f32_f16_e32 v68, v202
	v_cvt_f32_f16_e32 v69, v203
	v_mul_f32_e32 v68, 0xbfb8aa3b, v68
	v_mul_f32_e32 v69, 0xbfb8aa3b, v69
	v_exp_f32_e32 v68, v68
	v_exp_f32_e32 v69, v69
	s_nop 0
	v_pk_add_f32 v[68:69], v[68:69], 1.0 op_sel_hi:[1,0]
	s_nop 0
	v_div_scale_f32 v70, s[2:3], v69, v69, 1.0
	v_rcp_f32_e32 v71, v70
	s_nop 0
	v_fma_f32 v72, -v70, v71, 1.0
	v_fmac_f32_e32 v71, v72, v71
	v_div_scale_f32 v72, vcc, 1.0, v69, 1.0
	v_mul_f32_e32 v73, v72, v71
	v_fma_f32 v74, -v70, v73, v72
	v_fmac_f32_e32 v73, v74, v71
	v_fma_f32 v70, -v70, v73, v72
	v_div_fmas_f32 v70, v70, v71, v73
	v_div_fixup_f32 v69, v70, v69, 1.0
	v_div_scale_f32 v70, s[2:3], v68, v68, 1.0
	v_rcp_f32_e32 v71, v70
	s_nop 0
	v_fma_f32 v72, -v70, v71, 1.0
	v_fmac_f32_e32 v71, v72, v71
	v_div_scale_f32 v72, vcc, 1.0, v68, 1.0
	v_mul_f32_e32 v73, v72, v71
	v_fma_f32 v74, -v70, v73, v72
	v_fmac_f32_e32 v73, v74, v71
	v_fma_f32 v70, -v70, v73, v72
	v_div_fmas_f32 v70, v70, v71, v73
	v_div_fixup_f32 v68, v70, v68, 1.0
	v_pk_fma_f32 v[118:119], v[28:29], v[68:69], v[118:119]
	s_waitcnt vmcnt(18)
;   __device__ __forceinline__ const float* x() const { return (const float*)(const __attribute__((address_space(1))) float*)kp[0]; }
; __device__ __forceinline__ float sigmoidf_(float x) { return 1.f / (1.f + __expf(-x)); }
; __device__ __forceinline__ void phase_merge(const KP& p, char* smem, int* q, int xcc) {
;     ...
;           [&](int mi, int ni, int r, int row, int col, float v) {
;             const float gz = (float)G[(size_t)row * NU + col];
;             tot[mi][ni][r] += sigmoidf_(gz) * v;
	v_cvt_f32_f16_e32 v68, v204
	v_cvt_f32_f16_e32 v69, v205
	v_mul_f32_e32 v68, 0xbfb8aa3b, v68
	v_mul_f32_e32 v69, 0xbfb8aa3b, v69
	v_exp_f32_e32 v68, v68
	v_exp_f32_e32 v69, v69
	s_nop 0
	v_pk_add_f32 v[68:69], v[68:69], 1.0 op_sel_hi:[1,0]
	s_nop 0
	v_div_scale_f32 v70, s[2:3], v69, v69, 1.0
	v_rcp_f32_e32 v71, v70
	s_nop 0
	v_fma_f32 v72, -v70, v71, 1.0
	v_fmac_f32_e32 v71, v72, v71
	v_div_scale_f32 v72, vcc, 1.0, v69, 1.0
	v_mul_f32_e32 v73, v72, v71
	v_fma_f32 v74, -v70, v73, v72
	v_fmac_f32_e32 v73, v74, v71
	v_fma_f32 v70, -v70, v73, v72
	v_div_fmas_f32 v70, v70, v71, v73
	v_div_fixup_f32 v69, v70, v69, 1.0
	v_div_scale_f32 v70, s[2:3], v68, v68, 1.0
	v_rcp_f32_e32 v71, v70
	s_nop 0
	v_fma_f32 v72, -v70, v71, 1.0
	v_fmac_f32_e32 v71, v72, v71
	v_div_scale_f32 v72, vcc, 1.0, v68, 1.0
	v_mul_f32_e32 v73, v72, v71
	v_fma_f32 v74, -v70, v73, v72
	v_fmac_f32_e32 v73, v74, v71
	v_fma_f32 v70, -v70, v73, v72
	v_div_fmas_f32 v70, v70, v71, v73
	v_div_fixup_f32 v68, v70, v68, 1.0
	v_pk_fma_f32 v[116:117], v[30:31], v[68:69], v[116:117]
	s_waitcnt vmcnt(16)
	v_cvt_f32_f16_e32 v68, v206
	v_cvt_f32_f16_e32 v69, v207
	v_mul_f32_e32 v68, 0xbfb8aa3b, v68
	v_mul_f32_e32 v69, 0xbfb8aa3b, v69
	v_exp_f32_e32 v68, v68
	v_exp_f32_e32 v69, v69
	s_nop 0
	v_pk_add_f32 v[68:69], v[68:69], 1.0 op_sel_hi:[1,0]
	s_nop 0
	v_div_scale_f32 v70, s[2:3], v69, v69, 1.0
	v_rcp_f32_e32 v71, v70
	s_nop 0
	v_fma_f32 v72, -v70, v71, 1.0
	v_fmac_f32_e32 v71, v72, v71
	v_div_scale_f32 v72, vcc, 1.0, v69, 1.0
	v_mul_f32_e32 v73, v72, v71
	v_fma_f32 v74, -v70, v73, v72
	v_fmac_f32_e32 v73, v74, v71
	v_fma_f32 v70, -v70, v73, v72
	v_div_fmas_f32 v70, v70, v71, v73
	v_div_fixup_f32 v69, v70, v69, 1.0
	v_div_scale_f32 v70, s[2:3], v68, v68, 1.0
	v_rcp_f32_e32 v71, v70
	s_nop 0
	v_fma_f32 v72, -v70, v71, 1.0
	v_fmac_f32_e32 v71, v72, v71
	v_div_scale_f32 v72, vcc, 1.0, v68, 1.0
	v_mul_f32_e32 v73, v72, v71
	v_fma_f32 v74, -v70, v73, v72
	v_fmac_f32_e32 v73, v74, v71
	v_fma_f32 v70, -v70, v73, v72
	v_div_fmas_f32 v70, v70, v71, v73
	v_div_fixup_f32 v68, v70, v68, 1.0
	v_pk_fma_f32 v[114:115], v[32:33], v[68:69], v[114:115]
	s_waitcnt vmcnt(14)
	v_cvt_f32_f16_e32 v68, v208
	v_cvt_f32_f16_e32 v69, v209
	v_mul_f32_e32 v68, 0xbfb8aa3b, v68
	v_mul_f32_e32 v69, 0xbfb8aa3b, v69
	v_exp_f32_e32 v68, v68
	v_exp_f32_e32 v69, v69
	s_nop 0
	v_pk_add_f32 v[68:69], v[68:69], 1.0 op_sel_hi:[1,0]
	s_nop 0
	v_div_scale_f32 v70, s[2:3], v69, v69, 1.0
	v_rcp_f32_e32 v71, v70
	s_nop 0
	v_fma_f32 v72, -v70, v71, 1.0
	v_fmac_f32_e32 v71, v72, v71
	v_div_scale_f32 v72, vcc, 1.0, v69, 1.0
	v_mul_f32_e32 v73, v72, v71
	v_fma_f32 v74, -v70, v73, v72
	v_fmac_f32_e32 v73, v74, v71
	v_fma_f32 v70, -v70, v73, v72
	v_div_fmas_f32 v70, v70, v71, v73
	v_div_fixup_f32 v69, v70, v69, 1.0
	v_div_scale_f32 v70, s[2:3], v68, v68, 1.0
	v_rcp_f32_e32 v71, v70
	s_nop 0
	v_fma_f32 v72, -v70, v71, 1.0
	v_fmac_f32_e32 v71, v72, v71
	v_div_scale_f32 v72, vcc, 1.0, v68, 1.0
	v_mul_f32_e32 v73, v72, v71
	v_fma_f32 v74, -v70, v73, v72
	v_fmac_f32_e32 v73, v74, v71
	v_fma_f32 v70, -v70, v73, v72
	v_div_fmas_f32 v70, v70, v71, v73
	v_div_fixup_f32 v68, v70, v68, 1.0
	v_pk_fma_f32 v[112:113], v[2:3], v[68:69], v[112:113]
	s_waitcnt vmcnt(12)
	v_cvt_f32_f16_e32 v68, v210
	v_cvt_f32_f16_e32 v69, v211
	v_mul_f32_e32 v68, 0xbfb8aa3b, v68
	v_mul_f32_e32 v69, 0xbfb8aa3b, v69
	v_exp_f32_e32 v68, v68
	v_exp_f32_e32 v69, v69
	s_nop 0
	v_pk_add_f32 v[68:69], v[68:69], 1.0 op_sel_hi:[1,0]
	s_nop 0
	v_div_scale_f32 v70, s[2:3], v69, v69, 1.0
	v_rcp_f32_e32 v71, v70
	s_nop 0
	v_fma_f32 v72, -v70, v71, 1.0
	v_fmac_f32_e32 v71, v72, v71
	v_div_scale_f32 v72, vcc, 1.0, v69, 1.0
	v_mul_f32_e32 v73, v72, v71
	v_fma_f32 v74, -v70, v73, v72
	v_fmac_f32_e32 v73, v74, v71
	v_fma_f32 v70, -v70, v73, v72
	v_div_fmas_f32 v70, v70, v71, v73
	v_div_fixup_f32 v69, v70, v69, 1.0
	v_div_scale_f32 v70, s[2:3], v68, v68, 1.0
	v_rcp_f32_e32 v71, v70
	s_nop 0
	v_fma_f32 v72, -v70, v71, 1.0
	v_fmac_f32_e32 v71, v72, v71
	v_div_scale_f32 v72, vcc, 1.0, v68, 1.0
	v_mul_f32_e32 v73, v72, v71
	v_fma_f32 v74, -v70, v73, v72
	v_fmac_f32_e32 v73, v74, v71
	v_fma_f32 v70, -v70, v73, v72
	v_div_fmas_f32 v70, v70, v71, v73
	v_div_fixup_f32 v68, v70, v68, 1.0
	v_pk_fma_f32 v[110:111], v[4:5], v[68:69], v[110:111]
	s_waitcnt vmcnt(10)
	v_cvt_f32_f16_e32 v68, v212
	v_cvt_f32_f16_e32 v69, v213
	v_mul_f32_e32 v68, 0xbfb8aa3b, v68
	v_mul_f32_e32 v69, 0xbfb8aa3b, v69
	v_exp_f32_e32 v68, v68
	v_exp_f32_e32 v69, v69
	s_nop 0
	v_pk_add_f32 v[68:69], v[68:69], 1.0 op_sel_hi:[1,0]
	s_nop 0
	v_div_scale_f32 v70, s[2:3], v69, v69, 1.0
	v_rcp_f32_e32 v71, v70
	s_nop 0
	v_fma_f32 v72, -v70, v71, 1.0
	v_fmac_f32_e32 v71, v72, v71
	v_div_scale_f32 v72, vcc, 1.0, v69, 1.0
	v_mul_f32_e32 v73, v72, v71
	v_fma_f32 v74, -v70, v73, v72
	v_fmac_f32_e32 v73, v74, v71
	v_fma_f32 v70, -v70, v73, v72
	v_div_fmas_f32 v70, v70, v71, v73
	v_div_fixup_f32 v69, v70, v69, 1.0
	v_div_scale_f32 v70, s[2:3], v68, v68, 1.0
	v_rcp_f32_e32 v71, v70
	s_nop 0
	v_fma_f32 v72, -v70, v71, 1.0
	v_fmac_f32_e32 v71, v72, v71
	v_div_scale_f32 v72, vcc, 1.0, v68, 1.0
	v_mul_f32_e32 v73, v72, v71
	v_fma_f32 v74, -v70, v73, v72
	v_fmac_f32_e32 v73, v74, v71
	v_fma_f32 v70, -v70, v73, v72
	v_div_fmas_f32 v70, v70, v71, v73
	v_div_fixup_f32 v68, v70, v68, 1.0
	v_pk_fma_f32 v[108:109], v[6:7], v[68:69], v[108:109]
	s_waitcnt vmcnt(8)
;   __device__ __forceinline__ const float* x() const { return (const float*)(const __attribute__((address_space(1))) float*)kp[0]; }
; __device__ __forceinline__ float sigmoidf_(float x) { return 1.f / (1.f + __expf(-x)); }
; __device__ __forceinline__ void phase_merge(const KP& p, char* smem, int* q, int xcc) {
;     ...
;           [&](int mi, int ni, int r, int row, int col, float v) {
;             const float gz = (float)G[(size_t)row * NU + col];
;             tot[mi][ni][r] += sigmoidf_(gz) * v;
	v_cvt_f32_f16_e32 v68, v214
	v_cvt_f32_f16_e32 v69, v215
	v_mul_f32_e32 v68, 0xbfb8aa3b, v68
	v_mul_f32_e32 v69, 0xbfb8aa3b, v69
	v_exp_f32_e32 v68, v68
	v_exp_f32_e32 v69, v69
	s_nop 0
	v_pk_add_f32 v[68:69], v[68:69], 1.0 op_sel_hi:[1,0]
	s_nop 0
	v_div_scale_f32 v70, s[2:3], v69, v69, 1.0
	v_rcp_f32_e32 v71, v70
	s_nop 0
	v_fma_f32 v72, -v70, v71, 1.0
	v_fmac_f32_e32 v71, v72, v71
	v_div_scale_f32 v72, vcc, 1.0, v69, 1.0
	v_mul_f32_e32 v73, v72, v71
	v_fma_f32 v74, -v70, v73, v72
	v_fmac_f32_e32 v73, v74, v71
	v_fma_f32 v70, -v70, v73, v72
	v_div_fmas_f32 v70, v70, v71, v73
	v_div_fixup_f32 v69, v70, v69, 1.0
	v_div_scale_f32 v70, s[2:3], v68, v68, 1.0
	v_rcp_f32_e32 v71, v70
	s_nop 0
	v_fma_f32 v72, -v70, v71, 1.0
	v_fmac_f32_e32 v71, v72, v71
	v_div_scale_f32 v72, vcc, 1.0, v68, 1.0
	v_mul_f32_e32 v73, v72, v71
	v_fma_f32 v74, -v70, v73, v72
	v_fmac_f32_e32 v73, v74, v71
	v_fma_f32 v70, -v70, v73, v72
	v_div_fmas_f32 v70, v70, v71, v73
	v_div_fixup_f32 v68, v70, v68, 1.0
	v_pk_fma_f32 v[106:107], v[8:9], v[68:69], v[106:107]
	s_waitcnt vmcnt(6)
	v_cvt_f32_f16_e32 v68, v216
	v_cvt_f32_f16_e32 v69, v217
	v_mul_f32_e32 v68, 0xbfb8aa3b, v68
	v_mul_f32_e32 v69, 0xbfb8aa3b, v69
	v_exp_f32_e32 v68, v68
	v_exp_f32_e32 v69, v69
	s_nop 0
	v_pk_add_f32 v[68:69], v[68:69], 1.0 op_sel_hi:[1,0]
	s_nop 0
	v_div_scale_f32 v70, s[2:3], v69, v69, 1.0
	v_rcp_f32_e32 v71, v70
	s_nop 0
	v_fma_f32 v72, -v70, v71, 1.0
	v_fmac_f32_e32 v71, v72, v71
	v_div_scale_f32 v72, vcc, 1.0, v69, 1.0
	v_mul_f32_e32 v73, v72, v71
	v_fma_f32 v74, -v70, v73, v72
	v_fmac_f32_e32 v73, v74, v71
	v_fma_f32 v70, -v70, v73, v72
	v_div_fmas_f32 v70, v70, v71, v73
	v_div_fixup_f32 v69, v70, v69, 1.0
	v_div_scale_f32 v70, s[2:3], v68, v68, 1.0
	v_rcp_f32_e32 v71, v70
	s_nop 0
	v_fma_f32 v72, -v70, v71, 1.0
	v_fmac_f32_e32 v71, v72, v71
	v_div_scale_f32 v72, vcc, 1.0, v68, 1.0
	v_mul_f32_e32 v73, v72, v71
	v_fma_f32 v74, -v70, v73, v72
	v_fmac_f32_e32 v73, v74, v71
	v_fma_f32 v70, -v70, v73, v72
	v_div_fmas_f32 v70, v70, v71, v73
	v_div_fixup_f32 v68, v70, v68, 1.0
	v_pk_fma_f32 v[104:105], v[10:11], v[68:69], v[104:105]
	s_waitcnt vmcnt(4)
	v_cvt_f32_f16_e32 v68, v218
	v_cvt_f32_f16_e32 v69, v219
	v_mul_f32_e32 v68, 0xbfb8aa3b, v68
	v_mul_f32_e32 v69, 0xbfb8aa3b, v69
	v_exp_f32_e32 v68, v68
	v_exp_f32_e32 v69, v69
	s_nop 0
	v_pk_add_f32 v[68:69], v[68:69], 1.0 op_sel_hi:[1,0]
	s_nop 0
	v_div_scale_f32 v70, s[2:3], v69, v69, 1.0
	v_rcp_f32_e32 v71, v70
	s_nop 0
	v_fma_f32 v72, -v70, v71, 1.0
	v_fmac_f32_e32 v71, v72, v71
	v_div_scale_f32 v72, vcc, 1.0, v69, 1.0
	v_mul_f32_e32 v73, v72, v71
	v_fma_f32 v74, -v70, v73, v72
	v_fmac_f32_e32 v73, v74, v71
	v_fma_f32 v70, -v70, v73, v72
	v_div_fmas_f32 v70, v70, v71, v73
	v_div_fixup_f32 v69, v70, v69, 1.0
	v_div_scale_f32 v70, s[2:3], v68, v68, 1.0
	v_rcp_f32_e32 v71, v70
	s_nop 0
	v_fma_f32 v72, -v70, v71, 1.0
	v_fmac_f32_e32 v71, v72, v71
	v_div_scale_f32 v72, vcc, 1.0, v68, 1.0
	v_mul_f32_e32 v73, v72, v71
	v_fma_f32 v74, -v70, v73, v72
	v_fmac_f32_e32 v73, v74, v71
	v_fma_f32 v70, -v70, v73, v72
	v_div_fmas_f32 v70, v70, v71, v73
	v_div_fixup_f32 v68, v70, v68, 1.0
	v_pk_fma_f32 v[102:103], v[12:13], v[68:69], v[102:103]
	s_waitcnt vmcnt(2)
	v_cvt_f32_f16_e32 v68, v220
	v_cvt_f32_f16_e32 v69, v221
	v_mul_f32_e32 v68, 0xbfb8aa3b, v68
	v_mul_f32_e32 v69, 0xbfb8aa3b, v69
	v_exp_f32_e32 v68, v68
	v_exp_f32_e32 v69, v69
	s_nop 0
	v_pk_add_f32 v[68:69], v[68:69], 1.0 op_sel_hi:[1,0]
	s_nop 0
	v_div_scale_f32 v70, s[2:3], v69, v69, 1.0
	v_rcp_f32_e32 v71, v70
	s_nop 0
	v_fma_f32 v72, -v70, v71, 1.0
	v_fmac_f32_e32 v71, v72, v71
	v_div_scale_f32 v72, vcc, 1.0, v69, 1.0
	v_mul_f32_e32 v73, v72, v71
	v_fma_f32 v74, -v70, v73, v72
	v_fmac_f32_e32 v73, v74, v71
	v_fma_f32 v70, -v70, v73, v72
	v_div_fmas_f32 v70, v70, v71, v73
	v_div_fixup_f32 v69, v70, v69, 1.0
	v_div_scale_f32 v70, s[2:3], v68, v68, 1.0
	v_rcp_f32_e32 v71, v70
	s_nop 0
	v_fma_f32 v72, -v70, v71, 1.0
	v_fmac_f32_e32 v71, v72, v71
	v_div_scale_f32 v72, vcc, 1.0, v68, 1.0
	v_mul_f32_e32 v73, v72, v71
	v_fma_f32 v74, -v70, v73, v72
	v_fmac_f32_e32 v73, v74, v71
	v_fma_f32 v70, -v70, v73, v72
	v_div_fmas_f32 v70, v70, v71, v73
	v_div_fixup_f32 v68, v70, v68, 1.0
	v_pk_fma_f32 v[100:101], v[14:15], v[68:69], v[100:101]
	s_waitcnt vmcnt(0)
	v_cvt_f32_f16_e32 v68, v222
	v_cvt_f32_f16_e32 v69, v223
	v_mul_f32_e32 v68, 0xbfb8aa3b, v68
	v_mul_f32_e32 v69, 0xbfb8aa3b, v69
	v_exp_f32_e32 v68, v68
	v_exp_f32_e32 v69, v69
	s_nop 0
	v_pk_add_f32 v[68:69], v[68:69], 1.0 op_sel_hi:[1,0]
	s_nop 0
	v_div_scale_f32 v70, s[2:3], v69, v69, 1.0
	v_rcp_f32_e32 v71, v70
	s_nop 0
	v_fma_f32 v72, -v70, v71, 1.0
	v_fmac_f32_e32 v71, v72, v71
	v_div_scale_f32 v72, vcc, 1.0, v69, 1.0
	v_mul_f32_e32 v73, v72, v71
	v_fma_f32 v74, -v70, v73, v72
	v_fmac_f32_e32 v73, v74, v71
	v_fma_f32 v70, -v70, v73, v72
	v_div_fmas_f32 v70, v70, v71, v73
	v_div_fixup_f32 v69, v70, v69, 1.0
	v_div_scale_f32 v70, s[2:3], v68, v68, 1.0
	v_rcp_f32_e32 v71, v70
	s_nop 0
	v_fma_f32 v72, -v70, v71, 1.0
	v_fmac_f32_e32 v71, v72, v71
	v_div_scale_f32 v72, vcc, 1.0, v68, 1.0
	v_mul_f32_e32 v73, v72, v71
	v_fma_f32 v74, -v70, v73, v72
	v_fmac_f32_e32 v73, v74, v71
	v_fma_f32 v70, -v70, v73, v72
	v_div_fmas_f32 v70, v70, v71, v73
	v_div_fixup_f32 v68, v70, v68, 1.0
	v_pk_fma_f32 v[98:99], v[16:17], v[68:69], v[98:99]
	s_cmp_lg_u32 s56, 3
	s_cbranch_scc1 .LBB0_1742
;   __device__ __forceinline__ const float* x() const { return (const float*)(const __attribute__((address_space(1))) float*)kp[0]; }
;   __device__ __forceinline__ half_t* mm() const { return (half_t*)(ws() + OFF_mm); }
; __device__ __forceinline__ void phase_merge(const KP& p, char* smem, int* q, int xcc) {
;     ...
;     int tidx = threadIdx.x;
;     asm volatile("" : "+v"(tidx));
;     const int lane = tidx & 63, wid = tidx >> 6, wm = wid >> 1, wn = wid & 1;
; #pragma unroll
;     for (int mi = 0; mi < 2; ++mi)
; #pragma unroll
;       for (int ni = 0; ni < 2; ++ni)
; #pragma unroll
;         for (int r = 0; r < 16; ++r) {
;           const int row = wm * 64 + mi * 32 + (r & 3) + 8 * (r >> 2) + 4 * (lane >> 5);
;           const int col = wn * 64 + ni * 32 + (lane & 31);
;           p.mm()[(size_t)(m0 + row) * DM + n0 + col] = (half_t)tot[mi][ni][r];
;         }
	v_mov_b32_e32 v0, v224
	v_ashrrev_i32_e32 v2, 1, v0
	v_and_b32_e32 v2, 0xffffffc0, v2
	v_lshrrev_b32_e32 v3, 3, v0
	v_add_u32_e32 v2, s14, v2
	v_and_or_b32 v2, v3, 4, v2
	v_and_b32_e32 v3, 31, v0
	v_bfe_u32 v4, v0, 6, 1
	v_lshlrev_b32_e32 v3, 1, v3
	v_lshl_or_b32 v3, v4, 21, v3
	v_lshl_add_u32 v4, v2, 6, v3
	s_lshr_b32 s2, s18, 6
	s_lshl_b32 s2, s2, 20
	s_add_u32 s2, s44, s2
	s_addc_u32 s3, s45, 0
	s_add_u32 s40, s2, 0x100000
	s_addc_u32 s41, s3, 0
	v_cvt_f16_f32_e32 v5, v160
	global_store_short v4, v5, s[2:3]
	v_cvt_f16_f32_e32 v6, v161
	global_store_short v4, v6, s[2:3] offset:64
	v_cvt_f16_f32_e32 v7, v158
	global_store_short v4, v7, s[2:3] offset:128
	v_cvt_f16_f32_e32 v8, v159
	global_store_short v4, v8, s[2:3] offset:192
	v_cvt_f16_f32_e32 v9, v156
	global_store_short v4, v9, s[2:3] offset:512
	v_cvt_f16_f32_e32 v10, v157
	global_store_short v4, v10, s[2:3] offset:576
	v_cvt_f16_f32_e32 v11, v154
	global_store_short v4, v11, s[2:3] offset:640
	v_cvt_f16_f32_e32 v12, v155
	global_store_short v4, v12, s[2:3] offset:704
	v_cvt_f16_f32_e32 v5, v152
	global_store_short v4, v5, s[2:3] offset:1024
	v_cvt_f16_f32_e32 v6, v153
	global_store_short v4, v6, s[2:3] offset:1088
	v_cvt_f16_f32_e32 v7, v150
	global_store_short v4, v7, s[2:3] offset:1152
	v_cvt_f16_f32_e32 v8, v151
	global_store_short v4, v8, s[2:3] offset:1216
	v_cvt_f16_f32_e32 v9, v148
	global_store_short v4, v9, s[2:3] offset:1536
	v_cvt_f16_f32_e32 v10, v149
	global_store_short v4, v10, s[2:3] offset:1600
	v_cvt_f16_f32_e32 v11, v146
	global_store_short v4, v11, s[2:3] offset:1664
	v_cvt_f16_f32_e32 v12, v147
	global_store_short v4, v12, s[2:3] offset:1728
	v_cvt_f16_f32_e32 v5, v144
	global_store_short v4, v5, s[40:41]
	v_cvt_f16_f32_e32 v6, v145
	global_store_short v4, v6, s[40:41] offset:64
	v_cvt_f16_f32_e32 v7, v142
	global_store_short v4, v7, s[40:41] offset:128
	v_cvt_f16_f32_e32 v8, v143
	global_store_short v4, v8, s[40:41] offset:192
	v_cvt_f16_f32_e32 v9, v140
	global_store_short v4, v9, s[40:41] offset:512
	v_cvt_f16_f32_e32 v10, v141
	global_store_short v4, v10, s[40:41] offset:576
	v_cvt_f16_f32_e32 v11, v138
	global_store_short v4, v11, s[40:41] offset:640
	v_cvt_f16_f32_e32 v12, v139
	global_store_short v4, v12, s[40:41] offset:704
	v_cvt_f16_f32_e32 v5, v136
	global_store_short v4, v5, s[40:41] offset:1024
	v_cvt_f16_f32_e32 v6, v137
	global_store_short v4, v6, s[40:41] offset:1088
	v_cvt_f16_f32_e32 v7, v134
	global_store_short v4, v7, s[40:41] offset:1152
	v_cvt_f16_f32_e32 v8, v135
	global_store_short v4, v8, s[40:41] offset:1216
	v_cvt_f16_f32_e32 v9, v132
	global_store_short v4, v9, s[40:41] offset:1536
	v_cvt_f16_f32_e32 v10, v133
	global_store_short v4, v10, s[40:41] offset:1600
	v_cvt_f16_f32_e32 v11, v130
	global_store_short v4, v11, s[40:41] offset:1664
	v_cvt_f16_f32_e32 v12, v131
	global_store_short v4, v12, s[40:41] offset:1728
	v_cvt_f16_f32_e32 v5, v128
	global_store_short v4, v5, s[2:3] offset:2048
	v_cvt_f16_f32_e32 v6, v129
	global_store_short v4, v6, s[2:3] offset:2112
	v_cvt_f16_f32_e32 v7, v126
	global_store_short v4, v7, s[2:3] offset:2176
	v_cvt_f16_f32_e32 v8, v127
	global_store_short v4, v8, s[2:3] offset:2240
	v_cvt_f16_f32_e32 v9, v124
	global_store_short v4, v9, s[2:3] offset:2560
	v_cvt_f16_f32_e32 v10, v125
	global_store_short v4, v10, s[2:3] offset:2624
	v_cvt_f16_f32_e32 v11, v122
	global_store_short v4, v11, s[2:3] offset:2688
	v_cvt_f16_f32_e32 v12, v123
	global_store_short v4, v12, s[2:3] offset:2752
	v_cvt_f16_f32_e32 v5, v120
	global_store_short v4, v5, s[2:3] offset:3072
	v_cvt_f16_f32_e32 v6, v121
	global_store_short v4, v6, s[2:3] offset:3136
	v_cvt_f16_f32_e32 v7, v118
	global_store_short v4, v7, s[2:3] offset:3200
	v_cvt_f16_f32_e32 v8, v119
	global_store_short v4, v8, s[2:3] offset:3264
	v_cvt_f16_f32_e32 v9, v116
	global_store_short v4, v9, s[2:3] offset:3584
	v_cvt_f16_f32_e32 v10, v117
	global_store_short v4, v10, s[2:3] offset:3648
	v_cvt_f16_f32_e32 v11, v114
	global_store_short v4, v11, s[2:3] offset:3712
	v_cvt_f16_f32_e32 v12, v115
	global_store_short v4, v12, s[2:3] offset:3776
	v_cvt_f16_f32_e32 v5, v112
	global_store_short v4, v5, s[40:41] offset:2048
	v_cvt_f16_f32_e32 v6, v113
	global_store_short v4, v6, s[40:41] offset:2112
	v_cvt_f16_f32_e32 v7, v110
	global_store_short v4, v7, s[40:41] offset:2176
	v_cvt_f16_f32_e32 v8, v111
	global_store_short v4, v8, s[40:41] offset:2240
	v_cvt_f16_f32_e32 v9, v108
	global_store_short v4, v9, s[40:41] offset:2560
	v_cvt_f16_f32_e32 v10, v109
	global_store_short v4, v10, s[40:41] offset:2624
	v_cvt_f16_f32_e32 v11, v106
	global_store_short v4, v11, s[40:41] offset:2688
	v_cvt_f16_f32_e32 v12, v107
	global_store_short v4, v12, s[40:41] offset:2752
	v_cvt_f16_f32_e32 v5, v104
	global_store_short v4, v5, s[40:41] offset:3072
	v_cvt_f16_f32_e32 v6, v105
	global_store_short v4, v6, s[40:41] offset:3136
	v_cvt_f16_f32_e32 v7, v102
	global_store_short v4, v7, s[40:41] offset:3200
	v_cvt_f16_f32_e32 v8, v103
	global_store_short v4, v8, s[40:41] offset:3264
	v_cvt_f16_f32_e32 v9, v100
	global_store_short v4, v9, s[40:41] offset:3584
	v_cvt_f16_f32_e32 v10, v101
	global_store_short v4, v10, s[40:41] offset:3648
	v_cvt_f16_f32_e32 v11, v98
	global_store_short v4, v11, s[40:41] offset:3712
	v_cvt_f16_f32_e32 v12, v99
	global_store_short v4, v12, s[40:41] offset:3776
	s_branch .LBB0_1731
